# s_setprio 1 around the S5 f32-MFMA bursts so MFMA issue wins arbitration over the partner wave's VALU
# baseline (speedup 1.0000x reference)
; template <bool FINAL>
; __device__ __forceinline__ void s5_wave(const Params& P, int j, int g, int idx0, int stride, char* ldsw) {
;     ...
; #pragma unroll 2
;   for (int t = 0; t < 64; ++t) {
;     uint32_t w[8];
;     w[0] = __builtin_amdgcn_readlane(u0.x, t); w[1] = __builtin_amdgcn_readlane(u0.y, t);
;     w[2] = __builtin_amdgcn_readlane(u0.z, t); w[3] = __builtin_amdgcn_readlane(u0.w, t);
;     w[4] = __builtin_amdgcn_readlane(u1.x, t); w[5] = __builtin_amdgcn_readlane(u1.y, t);
;     w[6] = __builtin_amdgcn_readlane(u1.z, t); w[7] = __builtin_amdgcn_readlane(u1.w, t);
;     f32x2 acc0 = (f32x2){lbr * hr - lbi * hi, lbr * hi + lbi * hr}, acc1 = (f32x2){0.f, 0.f};
; #pragma unroll
;     for (int q = 0; q < 8; ++q) {
;       float ua = __uint_as_float(w[q] << 16), ub = __uint_as_float(w[q] & 0xffff0000u);
;       acc0 = bb[2 * q] * (f32x2){ua, ua} + acc0;
;       acc1 = bb[2 * q + 1] * (f32x2){ub, ub} + acc1;
;     }
;     acc0 = acc0 + acc1;
;     hr = acc0.x; hi = acc0.y;
;     if (FINAL) hbuf[t * 68 + p] = pack2(hr, hi);
;   }
.LBB0_437:
	s_waitcnt vmcnt(0)
	v_lshlrev_b32_e32 v100, v108, v194
	v_lshlrev_b32_e32 v101, v108, v195
	v_lshlrev_b32_e32 v102, v108, v196
	v_lshlrev_b32_e32 v103, v108, v197
	v_lshlrev_b32_e32 v104, v108, v198
	v_lshlrev_b32_e32 v105, v108, v199
	v_lshlrev_b32_e32 v106, v108, v200
	v_lshlrev_b32_e32 v107, v108, v201
	v_and_b32_e32 v100, 0xffff0000, v100
	v_and_b32_e32 v101, 0xffff0000, v101
	v_and_b32_e32 v102, 0xffff0000, v102
	v_and_b32_e32 v103, 0xffff0000, v103
	v_and_b32_e32 v104, 0xffff0000, v104
	v_and_b32_e32 v105, 0xffff0000, v105
	v_and_b32_e32 v106, 0xffff0000, v106
	v_and_b32_e32 v107, 0xffff0000, v107
	s_setprio 1
	v_mfma_f32_32x32x2_f32 v[116:131], v100, v56, 0
	v_mfma_f32_32x32x2_f32 v[132:147], v100, v57, 0
	v_mfma_f32_32x32x2_f32 v[148:163], v100, v44, 0
	v_mfma_f32_32x32x2_f32 v[164:179], v100, v45, 0
	v_mfma_f32_32x32x2_f32 v[116:131], v101, v40, v[116:131]
	v_mfma_f32_32x32x2_f32 v[132:147], v101, v41, v[132:147]
	v_mfma_f32_32x32x2_f32 v[148:163], v101, v42, v[148:163]
	v_mfma_f32_32x32x2_f32 v[164:179], v101, v43, v[164:179]
	v_mfma_f32_32x32x2_f32 v[116:131], v102, v46, v[116:131]
	v_mfma_f32_32x32x2_f32 v[132:147], v102, v47, v[132:147]
	v_mfma_f32_32x32x2_f32 v[148:163], v102, v36, v[148:163]
	v_mfma_f32_32x32x2_f32 v[164:179], v102, v37, v[164:179]
	v_mfma_f32_32x32x2_f32 v[116:131], v103, v32, v[116:131]
	v_mfma_f32_32x32x2_f32 v[132:147], v103, v33, v[132:147]
	v_mfma_f32_32x32x2_f32 v[148:163], v103, v34, v[148:163]
	v_mfma_f32_32x32x2_f32 v[164:179], v103, v35, v[164:179]
	v_mfma_f32_32x32x2_f32 v[116:131], v104, v38, v[116:131]
	v_mfma_f32_32x32x2_f32 v[132:147], v104, v39, v[132:147]
	v_mfma_f32_32x32x2_f32 v[148:163], v104, v28, v[148:163]
	v_mfma_f32_32x32x2_f32 v[164:179], v104, v29, v[164:179]
	v_mfma_f32_32x32x2_f32 v[116:131], v105, v58, v[116:131]
	v_mfma_f32_32x32x2_f32 v[132:147], v105, v59, v[132:147]
	v_mfma_f32_32x32x2_f32 v[148:163], v105, v30, v[148:163]
	v_mfma_f32_32x32x2_f32 v[164:179], v105, v31, v[164:179]
	v_mfma_f32_32x32x2_f32 v[116:131], v106, v60, v[116:131]
	v_mfma_f32_32x32x2_f32 v[132:147], v106, v61, v[132:147]
	v_mfma_f32_32x32x2_f32 v[148:163], v106, v62, v[148:163]
	v_mfma_f32_32x32x2_f32 v[164:179], v106, v63, v[164:179]
	v_mfma_f32_32x32x2_f32 v[116:131], v107, v64, v[116:131]
	v_mfma_f32_32x32x2_f32 v[132:147], v107, v65, v[132:147]
	v_mfma_f32_32x32x2_f32 v[148:163], v107, v66, v[148:163]
	v_mfma_f32_32x32x2_f32 v[164:179], v107, v67, v[164:179]
	s_setprio 0
	s_nop 15
	s_nop 3
	v_permlane32_swap_b32_e32 v116, v148
	v_permlane32_swap_b32_e32 v132, v164
	v_permlane32_swap_b32_e32 v117, v149
	v_permlane32_swap_b32_e32 v133, v165
	v_permlane32_swap_b32_e32 v118, v150
	v_permlane32_swap_b32_e32 v134, v166
	v_permlane32_swap_b32_e32 v119, v151
	v_permlane32_swap_b32_e32 v135, v167
	v_permlane32_swap_b32_e32 v120, v152
	v_permlane32_swap_b32_e32 v136, v168
	v_permlane32_swap_b32_e32 v121, v153
	v_permlane32_swap_b32_e32 v137, v169
	v_permlane32_swap_b32_e32 v122, v154
	v_permlane32_swap_b32_e32 v138, v170
	v_permlane32_swap_b32_e32 v123, v155
	v_permlane32_swap_b32_e32 v139, v171
	v_permlane32_swap_b32_e32 v124, v156
	v_permlane32_swap_b32_e32 v140, v172
	v_permlane32_swap_b32_e32 v125, v157
	v_permlane32_swap_b32_e32 v141, v173
	v_permlane32_swap_b32_e32 v126, v158
	v_permlane32_swap_b32_e32 v142, v174
	v_permlane32_swap_b32_e32 v127, v159
	v_permlane32_swap_b32_e32 v143, v175
	v_permlane32_swap_b32_e32 v128, v160
	v_permlane32_swap_b32_e32 v144, v176
	v_permlane32_swap_b32_e32 v129, v161
	v_permlane32_swap_b32_e32 v145, v177
	v_permlane32_swap_b32_e32 v130, v162
	v_permlane32_swap_b32_e32 v146, v178
	v_permlane32_swap_b32_e32 v131, v163
	v_permlane32_swap_b32_e32 v147, v179
	v_fma_f32 v116, v52, v82, v116
	v_fma_f32 v132, v52, v83, v132
	v_fma_f32 v116, -v54, v83, v116
	v_fma_f32 v132, v54, v82, v132
	v_cvt_pk_bf16_f32 v109, v116, v132
	ds_write_b32 v91, v109 offset:0
	v_fma_f32 v117, v52, v116, v117
	v_fma_f32 v133, v52, v132, v133
	v_fma_f32 v117, -v54, v132, v117
	v_fma_f32 v133, v54, v116, v133
	v_cvt_pk_bf16_f32 v114, v117, v133
	ds_write_b32 v91, v114 offset:272
	v_fma_f32 v118, v52, v117, v118
	v_fma_f32 v134, v52, v133, v134
	v_fma_f32 v118, -v54, v133, v118
	v_fma_f32 v134, v54, v117, v134
	v_cvt_pk_bf16_f32 v109, v118, v134
	ds_write_b32 v91, v109 offset:544
	v_fma_f32 v119, v52, v118, v119
	v_fma_f32 v135, v52, v134, v135
	v_fma_f32 v119, -v54, v134, v119
	v_fma_f32 v135, v54, v118, v135
	v_cvt_pk_bf16_f32 v114, v119, v135
	ds_write_b32 v91, v114 offset:816
	v_fma_f32 v148, v52, v119, v148
	v_fma_f32 v164, v52, v135, v164
	v_fma_f32 v148, -v54, v135, v148
	v_fma_f32 v164, v54, v119, v164
	v_cvt_pk_bf16_f32 v109, v148, v164
	ds_write_b32 v91, v109 offset:1088
	v_fma_f32 v149, v52, v148, v149
	v_fma_f32 v165, v52, v164, v165
	v_fma_f32 v149, -v54, v164, v149
	v_fma_f32 v165, v54, v148, v165
	v_cvt_pk_bf16_f32 v114, v149, v165
	ds_write_b32 v91, v114 offset:1360
	v_fma_f32 v150, v52, v149, v150
	v_fma_f32 v166, v52, v165, v166
	v_fma_f32 v150, -v54, v165, v150
	v_fma_f32 v166, v54, v149, v166
	v_cvt_pk_bf16_f32 v109, v150, v166
	ds_write_b32 v91, v109 offset:1632
	v_fma_f32 v151, v52, v150, v151
	v_fma_f32 v167, v52, v166, v167
	v_fma_f32 v151, -v54, v166, v151
	v_fma_f32 v167, v54, v150, v167
	v_cvt_pk_bf16_f32 v114, v151, v167
	ds_write_b32 v91, v114 offset:1904
	v_fma_f32 v120, v52, v151, v120
	v_fma_f32 v136, v52, v167, v136
	v_fma_f32 v120, -v54, v167, v120
	v_fma_f32 v136, v54, v151, v136
	v_cvt_pk_bf16_f32 v109, v120, v136
	ds_write_b32 v91, v109 offset:2176
	v_fma_f32 v121, v52, v120, v121
	v_fma_f32 v137, v52, v136, v137
	v_fma_f32 v121, -v54, v136, v121
; template <bool FINAL>
; __device__ __forceinline__ void s5_wave(const Params& P, int j, int g, int idx0, int stride, char* ldsw) {
;     ...
; #pragma unroll 2
;   for (int t = 0; t < 64; ++t) {
;     uint32_t w[8];
;     w[0] = __builtin_amdgcn_readlane(u0.x, t); w[1] = __builtin_amdgcn_readlane(u0.y, t);
;     w[2] = __builtin_amdgcn_readlane(u0.z, t); w[3] = __builtin_amdgcn_readlane(u0.w, t);
;     w[4] = __builtin_amdgcn_readlane(u1.x, t); w[5] = __builtin_amdgcn_readlane(u1.y, t);
;     w[6] = __builtin_amdgcn_readlane(u1.z, t); w[7] = __builtin_amdgcn_readlane(u1.w, t);
;     f32x2 acc0 = (f32x2){lbr * hr - lbi * hi, lbr * hi + lbi * hr}, acc1 = (f32x2){0.f, 0.f};
; #pragma unroll
;     for (int q = 0; q < 8; ++q) {
;       float ua = __uint_as_float(w[q] << 16), ub = __uint_as_float(w[q] & 0xffff0000u);
;       acc0 = bb[2 * q] * (f32x2){ua, ua} + acc0;
;       acc1 = bb[2 * q + 1] * (f32x2){ub, ub} + acc1;
;     }
;     acc0 = acc0 + acc1;
;     hr = acc0.x; hi = acc0.y;
;     if (FINAL) hbuf[t * 68 + p] = pack2(hr, hi);
;   }
	v_fma_f32 v137, v54, v120, v137
	v_cvt_pk_bf16_f32 v114, v121, v137
	ds_write_b32 v91, v114 offset:2448
	v_fma_f32 v122, v52, v121, v122
	v_fma_f32 v138, v52, v137, v138
	v_fma_f32 v122, -v54, v137, v122
	v_fma_f32 v138, v54, v121, v138
	v_cvt_pk_bf16_f32 v109, v122, v138
	ds_write_b32 v91, v109 offset:2720
	v_fma_f32 v123, v52, v122, v123
	v_fma_f32 v139, v52, v138, v139
	v_fma_f32 v123, -v54, v138, v123
	v_fma_f32 v139, v54, v122, v139
	v_cvt_pk_bf16_f32 v114, v123, v139
	ds_write_b32 v91, v114 offset:2992
	v_fma_f32 v152, v52, v123, v152
	v_fma_f32 v168, v52, v139, v168
	v_fma_f32 v152, -v54, v139, v152
	v_fma_f32 v168, v54, v123, v168
	v_cvt_pk_bf16_f32 v109, v152, v168
	ds_write_b32 v91, v109 offset:3264
	v_fma_f32 v153, v52, v152, v153
	v_fma_f32 v169, v52, v168, v169
	v_fma_f32 v153, -v54, v168, v153
	v_fma_f32 v169, v54, v152, v169
	v_cvt_pk_bf16_f32 v114, v153, v169
	ds_write_b32 v91, v114 offset:3536
	v_fma_f32 v154, v52, v153, v154
	v_fma_f32 v170, v52, v169, v170
	v_fma_f32 v154, -v54, v169, v154
	v_fma_f32 v170, v54, v153, v170
	v_cvt_pk_bf16_f32 v109, v154, v170
	ds_write_b32 v91, v109 offset:3808
	v_fma_f32 v155, v52, v154, v155
	v_fma_f32 v171, v52, v170, v171
	v_fma_f32 v155, -v54, v170, v155
	v_fma_f32 v171, v54, v154, v171
	v_cvt_pk_bf16_f32 v114, v155, v171
	ds_write_b32 v91, v114 offset:4080
	v_fma_f32 v124, v52, v155, v124
	v_fma_f32 v140, v52, v171, v140
	v_fma_f32 v124, -v54, v171, v124
	v_fma_f32 v140, v54, v155, v140
	v_cvt_pk_bf16_f32 v109, v124, v140
	ds_write_b32 v91, v109 offset:4352
	v_fma_f32 v125, v52, v124, v125
	v_fma_f32 v141, v52, v140, v141
	v_fma_f32 v125, -v54, v140, v125
	v_fma_f32 v141, v54, v124, v141
	v_cvt_pk_bf16_f32 v114, v125, v141
	ds_write_b32 v91, v114 offset:4624
	v_fma_f32 v126, v52, v125, v126
	v_fma_f32 v142, v52, v141, v142
	v_fma_f32 v126, -v54, v141, v126
	v_fma_f32 v142, v54, v125, v142
	v_cvt_pk_bf16_f32 v109, v126, v142
	ds_write_b32 v91, v109 offset:4896
	v_fma_f32 v127, v52, v126, v127
	v_fma_f32 v143, v52, v142, v143
	v_fma_f32 v127, -v54, v142, v127
	v_fma_f32 v143, v54, v126, v143
	v_cvt_pk_bf16_f32 v114, v127, v143
	ds_write_b32 v91, v114 offset:5168
	v_fma_f32 v156, v52, v127, v156
	v_fma_f32 v172, v52, v143, v172
	v_fma_f32 v156, -v54, v143, v156
	v_fma_f32 v172, v54, v127, v172
	v_cvt_pk_bf16_f32 v109, v156, v172
	ds_write_b32 v91, v109 offset:5440
	v_fma_f32 v157, v52, v156, v157
	v_fma_f32 v173, v52, v172, v173
	v_fma_f32 v157, -v54, v172, v157
	v_fma_f32 v173, v54, v156, v173
	v_cvt_pk_bf16_f32 v114, v157, v173
	ds_write_b32 v91, v114 offset:5712
	v_fma_f32 v158, v52, v157, v158
	v_fma_f32 v174, v52, v173, v174
	v_fma_f32 v158, -v54, v173, v158
	v_fma_f32 v174, v54, v157, v174
	v_cvt_pk_bf16_f32 v109, v158, v174
	ds_write_b32 v91, v109 offset:5984
	v_fma_f32 v159, v52, v158, v159
	v_fma_f32 v175, v52, v174, v175
	v_fma_f32 v159, -v54, v174, v159
	v_fma_f32 v175, v54, v158, v175
	v_cvt_pk_bf16_f32 v114, v159, v175
	ds_write_b32 v91, v114 offset:6256
	v_fma_f32 v128, v52, v159, v128
	v_fma_f32 v144, v52, v175, v144
	v_fma_f32 v128, -v54, v175, v128
	v_fma_f32 v144, v54, v159, v144
	v_cvt_pk_bf16_f32 v109, v128, v144
	ds_write_b32 v91, v109 offset:6528
	v_fma_f32 v129, v52, v128, v129
	v_fma_f32 v145, v52, v144, v145
	v_fma_f32 v129, -v54, v144, v129
	v_fma_f32 v145, v54, v128, v145
	v_cvt_pk_bf16_f32 v114, v129, v145
	ds_write_b32 v91, v114 offset:6800
	v_fma_f32 v130, v52, v129, v130
	v_fma_f32 v146, v52, v145, v146
	v_fma_f32 v130, -v54, v145, v130
	v_fma_f32 v146, v54, v129, v146
	v_cvt_pk_bf16_f32 v109, v130, v146
	ds_write_b32 v91, v109 offset:7072
	v_fma_f32 v131, v52, v130, v131
	v_fma_f32 v147, v52, v146, v147
	v_fma_f32 v131, -v54, v146, v131
	v_fma_f32 v147, v54, v130, v147
	v_cvt_pk_bf16_f32 v114, v131, v147
	ds_write_b32 v91, v114 offset:7344
	v_fma_f32 v160, v52, v131, v160
	v_fma_f32 v176, v52, v147, v176
	v_fma_f32 v160, -v54, v147, v160
	v_fma_f32 v176, v54, v131, v176
	v_cvt_pk_bf16_f32 v109, v160, v176
	ds_write_b32 v91, v109 offset:7616
	v_fma_f32 v161, v52, v160, v161
	v_fma_f32 v177, v52, v176, v177
	v_fma_f32 v161, -v54, v176, v161
	v_fma_f32 v177, v54, v160, v177
	v_cvt_pk_bf16_f32 v114, v161, v177
	ds_write_b32 v91, v114 offset:7888
	v_fma_f32 v162, v52, v161, v162
	v_fma_f32 v178, v52, v177, v178
	v_fma_f32 v162, -v54, v177, v162
	v_fma_f32 v178, v54, v161, v178
	v_cvt_pk_bf16_f32 v109, v162, v178
	ds_write_b32 v91, v109 offset:8160
	v_fma_f32 v163, v52, v162, v163
	v_fma_f32 v179, v52, v178, v179
	v_fma_f32 v163, -v54, v178, v163
	v_fma_f32 v179, v54, v162, v179
	v_cvt_pk_bf16_f32 v114, v163, v179
	ds_write_b32 v91, v114 offset:8432
	v_mov_b32_e32 v82, v163
	v_mov_b32_e32 v83, v179
	v_lshlrev_b32_e32 v100, v108, v202
	v_lshlrev_b32_e32 v101, v108, v203
	v_lshlrev_b32_e32 v102, v108, v204
	v_lshlrev_b32_e32 v103, v108, v205
	v_lshlrev_b32_e32 v104, v108, v242
	v_lshlrev_b32_e32 v105, v108, v243
	v_lshlrev_b32_e32 v106, v108, v244
	v_lshlrev_b32_e32 v107, v108, v245
	v_and_b32_e32 v100, 0xffff0000, v100
	v_and_b32_e32 v101, 0xffff0000, v101
	v_and_b32_e32 v102, 0xffff0000, v102
	v_and_b32_e32 v103, 0xffff0000, v103
	v_and_b32_e32 v104, 0xffff0000, v104
	v_and_b32_e32 v105, 0xffff0000, v105
	v_and_b32_e32 v106, 0xffff0000, v106
	v_and_b32_e32 v107, 0xffff0000, v107
	s_setprio 1
	v_mfma_f32_32x32x2_f32 v[116:131], v100, v56, 0
	v_mfma_f32_32x32x2_f32 v[132:147], v100, v57, 0
	v_mfma_f32_32x32x2_f32 v[148:163], v100, v44, 0
	v_mfma_f32_32x32x2_f32 v[164:179], v100, v45, 0
	v_mfma_f32_32x32x2_f32 v[116:131], v101, v40, v[116:131]
	v_mfma_f32_32x32x2_f32 v[132:147], v101, v41, v[132:147]
	v_mfma_f32_32x32x2_f32 v[148:163], v101, v42, v[148:163]
; template <bool FINAL>
; __device__ __forceinline__ void s5_wave(const Params& P, int j, int g, int idx0, int stride, char* ldsw) {
;     ...
;   for (int t = 0; t < 64; ++t) {
;     uint32_t w[8];
;     w[0] = __builtin_amdgcn_readlane(u0.x, t); w[1] = __builtin_amdgcn_readlane(u0.y, t);
;     w[2] = __builtin_amdgcn_readlane(u0.z, t); w[3] = __builtin_amdgcn_readlane(u0.w, t);
;     w[4] = __builtin_amdgcn_readlane(u1.x, t); w[5] = __builtin_amdgcn_readlane(u1.y, t);
;     w[6] = __builtin_amdgcn_readlane(u1.z, t); w[7] = __builtin_amdgcn_readlane(u1.w, t);
;     f32x2 acc0 = (f32x2){lbr * hr - lbi * hi, lbr * hi + lbi * hr}, acc1 = (f32x2){0.f, 0.f};
; #pragma unroll
;     for (int q = 0; q < 8; ++q) {
;       float ua = __uint_as_float(w[q] << 16), ub = __uint_as_float(w[q] & 0xffff0000u);
;       acc0 = bb[2 * q] * (f32x2){ua, ua} + acc0;
;       acc1 = bb[2 * q + 1] * (f32x2){ub, ub} + acc1;
;     }
;     acc0 = acc0 + acc1;
;     hr = acc0.x; hi = acc0.y;
;     if (FINAL) hbuf[t * 68 + p] = pack2(hr, hi);
;   }
	v_mfma_f32_32x32x2_f32 v[164:179], v101, v43, v[164:179]
	v_mfma_f32_32x32x2_f32 v[116:131], v102, v46, v[116:131]
	v_mfma_f32_32x32x2_f32 v[132:147], v102, v47, v[132:147]
	v_mfma_f32_32x32x2_f32 v[148:163], v102, v36, v[148:163]
	v_mfma_f32_32x32x2_f32 v[164:179], v102, v37, v[164:179]
	v_mfma_f32_32x32x2_f32 v[116:131], v103, v32, v[116:131]
	v_mfma_f32_32x32x2_f32 v[132:147], v103, v33, v[132:147]
	v_mfma_f32_32x32x2_f32 v[148:163], v103, v34, v[148:163]
	v_mfma_f32_32x32x2_f32 v[164:179], v103, v35, v[164:179]
	v_mfma_f32_32x32x2_f32 v[116:131], v104, v38, v[116:131]
	v_mfma_f32_32x32x2_f32 v[132:147], v104, v39, v[132:147]
	v_mfma_f32_32x32x2_f32 v[148:163], v104, v28, v[148:163]
	v_mfma_f32_32x32x2_f32 v[164:179], v104, v29, v[164:179]
	v_mfma_f32_32x32x2_f32 v[116:131], v105, v58, v[116:131]
	v_mfma_f32_32x32x2_f32 v[132:147], v105, v59, v[132:147]
	v_mfma_f32_32x32x2_f32 v[148:163], v105, v30, v[148:163]
	v_mfma_f32_32x32x2_f32 v[164:179], v105, v31, v[164:179]
	v_mfma_f32_32x32x2_f32 v[116:131], v106, v60, v[116:131]
	v_mfma_f32_32x32x2_f32 v[132:147], v106, v61, v[132:147]
	v_mfma_f32_32x32x2_f32 v[148:163], v106, v62, v[148:163]
	v_mfma_f32_32x32x2_f32 v[164:179], v106, v63, v[164:179]
	v_mfma_f32_32x32x2_f32 v[116:131], v107, v64, v[116:131]
	v_mfma_f32_32x32x2_f32 v[132:147], v107, v65, v[132:147]
	v_mfma_f32_32x32x2_f32 v[148:163], v107, v66, v[148:163]
	v_mfma_f32_32x32x2_f32 v[164:179], v107, v67, v[164:179]
	s_setprio 0
	s_nop 15
	s_nop 3
	v_permlane32_swap_b32_e32 v116, v148
	v_permlane32_swap_b32_e32 v132, v164
	v_permlane32_swap_b32_e32 v117, v149
	v_permlane32_swap_b32_e32 v133, v165
	v_permlane32_swap_b32_e32 v118, v150
	v_permlane32_swap_b32_e32 v134, v166
	v_permlane32_swap_b32_e32 v119, v151
	v_permlane32_swap_b32_e32 v135, v167
	v_permlane32_swap_b32_e32 v120, v152
	v_permlane32_swap_b32_e32 v136, v168
	v_permlane32_swap_b32_e32 v121, v153
	v_permlane32_swap_b32_e32 v137, v169
	v_permlane32_swap_b32_e32 v122, v154
	v_permlane32_swap_b32_e32 v138, v170
	v_permlane32_swap_b32_e32 v123, v155
	v_permlane32_swap_b32_e32 v139, v171
	v_permlane32_swap_b32_e32 v124, v156
	v_permlane32_swap_b32_e32 v140, v172
	v_permlane32_swap_b32_e32 v125, v157
	v_permlane32_swap_b32_e32 v141, v173
	v_permlane32_swap_b32_e32 v126, v158
	v_permlane32_swap_b32_e32 v142, v174
	v_permlane32_swap_b32_e32 v127, v159
	v_permlane32_swap_b32_e32 v143, v175
	v_permlane32_swap_b32_e32 v128, v160
	v_permlane32_swap_b32_e32 v144, v176
	v_permlane32_swap_b32_e32 v129, v161
	v_permlane32_swap_b32_e32 v145, v177
	v_permlane32_swap_b32_e32 v130, v162
	v_permlane32_swap_b32_e32 v146, v178
	v_permlane32_swap_b32_e32 v131, v163
	v_permlane32_swap_b32_e32 v147, v179
	v_fma_f32 v116, v52, v82, v116
	v_fma_f32 v132, v52, v83, v132
	v_fma_f32 v116, -v54, v83, v116
	v_fma_f32 v132, v54, v82, v132
	v_cvt_pk_bf16_f32 v109, v116, v132
	ds_write_b32 v91, v109 offset:8704
	v_fma_f32 v117, v52, v116, v117
	v_fma_f32 v133, v52, v132, v133
	v_fma_f32 v117, -v54, v132, v117
	v_fma_f32 v133, v54, v116, v133
	v_cvt_pk_bf16_f32 v114, v117, v133
	ds_write_b32 v91, v114 offset:8976
	v_fma_f32 v118, v52, v117, v118
	v_fma_f32 v134, v52, v133, v134
	v_fma_f32 v118, -v54, v133, v118
	v_fma_f32 v134, v54, v117, v134
	v_cvt_pk_bf16_f32 v109, v118, v134
	ds_write_b32 v91, v109 offset:9248
	v_fma_f32 v119, v52, v118, v119
	v_fma_f32 v135, v52, v134, v135
	v_fma_f32 v119, -v54, v134, v119
	v_fma_f32 v135, v54, v118, v135
	v_cvt_pk_bf16_f32 v114, v119, v135
	ds_write_b32 v91, v114 offset:9520
	v_fma_f32 v148, v52, v119, v148
	v_fma_f32 v164, v52, v135, v164
	v_fma_f32 v148, -v54, v135, v148
	v_fma_f32 v164, v54, v119, v164
	v_cvt_pk_bf16_f32 v109, v148, v164
	ds_write_b32 v91, v109 offset:9792
	v_fma_f32 v149, v52, v148, v149
	v_fma_f32 v165, v52, v164, v165
	v_fma_f32 v149, -v54, v164, v149
	v_fma_f32 v165, v54, v148, v165
	v_cvt_pk_bf16_f32 v114, v149, v165
	ds_write_b32 v91, v114 offset:10064
	v_fma_f32 v150, v52, v149, v150
	v_fma_f32 v166, v52, v165, v166
	v_fma_f32 v150, -v54, v165, v150
	v_fma_f32 v166, v54, v149, v166
	v_cvt_pk_bf16_f32 v109, v150, v166
	ds_write_b32 v91, v109 offset:10336
	v_fma_f32 v151, v52, v150, v151
	v_fma_f32 v167, v52, v166, v167
	v_fma_f32 v151, -v54, v166, v151
	v_fma_f32 v167, v54, v150, v167
	v_cvt_pk_bf16_f32 v114, v151, v167
	ds_write_b32 v91, v114 offset:10608
	v_fma_f32 v120, v52, v151, v120
	v_fma_f32 v136, v52, v167, v136
	v_fma_f32 v120, -v54, v167, v120
	v_fma_f32 v136, v54, v151, v136
	v_cvt_pk_bf16_f32 v109, v120, v136
	ds_write_b32 v91, v109 offset:10880
	v_fma_f32 v121, v52, v120, v121
	v_fma_f32 v137, v52, v136, v137
	v_fma_f32 v121, -v54, v136, v121
	v_fma_f32 v137, v54, v120, v137
	v_cvt_pk_bf16_f32 v114, v121, v137
	ds_write_b32 v91, v114 offset:11152
	v_fma_f32 v122, v52, v121, v122
	v_fma_f32 v138, v52, v137, v138
	v_fma_f32 v122, -v54, v137, v122
	v_fma_f32 v138, v54, v121, v138
	v_cvt_pk_bf16_f32 v109, v122, v138
	ds_write_b32 v91, v109 offset:11424
	v_fma_f32 v123, v52, v122, v123
	v_fma_f32 v139, v52, v138, v139
	v_fma_f32 v123, -v54, v138, v123
	v_fma_f32 v139, v54, v122, v139
	v_cvt_pk_bf16_f32 v114, v123, v139
	ds_write_b32 v91, v114 offset:11696
	v_fma_f32 v152, v52, v123, v152
	v_fma_f32 v168, v52, v139, v168
	v_fma_f32 v152, -v54, v139, v152
	v_fma_f32 v168, v54, v123, v168
	v_cvt_pk_bf16_f32 v109, v152, v168
	ds_write_b32 v91, v109 offset:11968
	v_fma_f32 v153, v52, v152, v153
	v_fma_f32 v169, v52, v168, v169
	v_fma_f32 v153, -v54, v168, v153
	v_fma_f32 v169, v54, v152, v169
	v_cvt_pk_bf16_f32 v114, v153, v169
	ds_write_b32 v91, v114 offset:12240
	v_fma_f32 v154, v52, v153, v154
	v_fma_f32 v170, v52, v169, v170
; template <bool FINAL>
; __device__ __forceinline__ void s5_wave(const Params& P, int j, int g, int idx0, int stride, char* ldsw) {
;     ...
;     f32x2 acc0 = (f32x2){lbr * hr - lbi * hi, lbr * hi + lbi * hr}, acc1 = (f32x2){0.f, 0.f};
; #pragma unroll
;     for (int q = 0; q < 8; ++q) {
;       float ua = __uint_as_float(w[q] << 16), ub = __uint_as_float(w[q] & 0xffff0000u);
;       acc0 = bb[2 * q] * (f32x2){ua, ua} + acc0;
;       acc1 = bb[2 * q + 1] * (f32x2){ub, ub} + acc1;
;     }
;     acc0 = acc0 + acc1;
;     hr = acc0.x; hi = acc0.y;
;     if (FINAL) hbuf[t * 68 + p] = pack2(hr, hi);
;     ...
;     u16* zs = reinterpret_cast<u16*>(P.ws + OFF_BIG + (size_t)T * 1280 * 2);
;     uint2 uw[4];
; #pragma unroll
;     for (int mt = 0; mt < 4; ++mt)
;       uw[mt] = *reinterpret_cast<const uint2*>(Zo + (rowbase + mt * 16 + fr) * 1280 + 768 + g * 16 + 4 * fq);
; #pragma unroll
;     for (int mt = 0; mt < 4; ++mt) {
;       f32x4 y = {0.f, 0.f, 0.f, 0.f};
; #pragma unroll
;       for (int ks = 0; ks < 4; ++ks) {
;         bf16x8 a = *reinterpret_cast<const bf16x8*>(hbuf + (mt * 16 + fr) * 68 + ks * 16 + fq * 4);
;         y = __builtin_amdgcn_mfma_f32_16x16x32_bf16(bc[ks], a, y, 0, 0, 0);
	v_fma_f32 v154, -v54, v169, v154
	v_fma_f32 v170, v54, v153, v170
	v_cvt_pk_bf16_f32 v109, v154, v170
	ds_write_b32 v91, v109 offset:12512
	v_fma_f32 v155, v52, v154, v155
	v_fma_f32 v171, v52, v170, v171
	v_fma_f32 v155, -v54, v170, v155
	v_fma_f32 v171, v54, v154, v171
	v_cvt_pk_bf16_f32 v114, v155, v171
	ds_write_b32 v91, v114 offset:12784
	v_fma_f32 v124, v52, v155, v124
	v_fma_f32 v140, v52, v171, v140
	v_fma_f32 v124, -v54, v171, v124
	v_fma_f32 v140, v54, v155, v140
	v_cvt_pk_bf16_f32 v109, v124, v140
	ds_write_b32 v91, v109 offset:13056
	v_fma_f32 v125, v52, v124, v125
	v_fma_f32 v141, v52, v140, v141
	v_fma_f32 v125, -v54, v140, v125
	v_fma_f32 v141, v54, v124, v141
	v_cvt_pk_bf16_f32 v114, v125, v141
	ds_write_b32 v91, v114 offset:13328
	v_fma_f32 v126, v52, v125, v126
	v_fma_f32 v142, v52, v141, v142
	v_fma_f32 v126, -v54, v141, v126
	v_fma_f32 v142, v54, v125, v142
	v_cvt_pk_bf16_f32 v109, v126, v142
	ds_write_b32 v91, v109 offset:13600
	v_fma_f32 v127, v52, v126, v127
	v_fma_f32 v143, v52, v142, v143
	v_fma_f32 v127, -v54, v142, v127
	v_fma_f32 v143, v54, v126, v143
	v_cvt_pk_bf16_f32 v114, v127, v143
	ds_write_b32 v91, v114 offset:13872
	v_fma_f32 v156, v52, v127, v156
	v_fma_f32 v172, v52, v143, v172
	v_fma_f32 v156, -v54, v143, v156
	v_fma_f32 v172, v54, v127, v172
	v_cvt_pk_bf16_f32 v109, v156, v172
	ds_write_b32 v91, v109 offset:14144
	v_fma_f32 v157, v52, v156, v157
	v_fma_f32 v173, v52, v172, v173
	v_fma_f32 v157, -v54, v172, v157
	v_fma_f32 v173, v54, v156, v173
	v_cvt_pk_bf16_f32 v114, v157, v173
	ds_write_b32 v91, v114 offset:14416
	v_fma_f32 v158, v52, v157, v158
	v_fma_f32 v174, v52, v173, v174
	v_fma_f32 v158, -v54, v173, v158
	v_fma_f32 v174, v54, v157, v174
	v_cvt_pk_bf16_f32 v109, v158, v174
	ds_write_b32 v91, v109 offset:14688
	v_fma_f32 v159, v52, v158, v159
	v_fma_f32 v175, v52, v174, v175
	v_fma_f32 v159, -v54, v174, v159
	v_fma_f32 v175, v54, v158, v175
	v_cvt_pk_bf16_f32 v114, v159, v175
	ds_write_b32 v91, v114 offset:14960
	v_fma_f32 v128, v52, v159, v128
	v_fma_f32 v144, v52, v175, v144
	v_fma_f32 v128, -v54, v175, v128
	v_fma_f32 v144, v54, v159, v144
	v_cvt_pk_bf16_f32 v109, v128, v144
	ds_write_b32 v91, v109 offset:15232
	v_fma_f32 v129, v52, v128, v129
	v_fma_f32 v145, v52, v144, v145
	v_fma_f32 v129, -v54, v144, v129
	v_fma_f32 v145, v54, v128, v145
	v_cvt_pk_bf16_f32 v114, v129, v145
	ds_write_b32 v91, v114 offset:15504
	v_fma_f32 v130, v52, v129, v130
	v_fma_f32 v146, v52, v145, v146
	v_fma_f32 v130, -v54, v145, v130
	v_fma_f32 v146, v54, v129, v146
	v_cvt_pk_bf16_f32 v109, v130, v146
	ds_write_b32 v91, v109 offset:15776
	v_fma_f32 v131, v52, v130, v131
	v_fma_f32 v147, v52, v146, v147
	v_fma_f32 v131, -v54, v146, v131
	v_fma_f32 v147, v54, v130, v147
	v_cvt_pk_bf16_f32 v114, v131, v147
	ds_write_b32 v91, v114 offset:16048
	v_fma_f32 v160, v52, v131, v160
	v_fma_f32 v176, v52, v147, v176
	v_fma_f32 v160, -v54, v147, v160
	v_fma_f32 v176, v54, v131, v176
	v_cvt_pk_bf16_f32 v109, v160, v176
	ds_write_b32 v91, v109 offset:16320
	v_fma_f32 v161, v52, v160, v161
	v_fma_f32 v177, v52, v176, v177
	v_fma_f32 v161, -v54, v176, v161
	v_fma_f32 v177, v54, v160, v177
	v_cvt_pk_bf16_f32 v114, v161, v177
	ds_write_b32 v91, v114 offset:16592
	v_fma_f32 v162, v52, v161, v162
	v_fma_f32 v178, v52, v177, v178
	v_fma_f32 v162, -v54, v177, v162
	v_fma_f32 v178, v54, v161, v178
	v_cvt_pk_bf16_f32 v109, v162, v178
	ds_write_b32 v91, v109 offset:16864
	v_fma_f32 v163, v52, v162, v163
	v_fma_f32 v179, v52, v178, v179
	v_fma_f32 v163, -v54, v178, v163
	v_fma_f32 v179, v54, v162, v179
	v_cvt_pk_bf16_f32 v114, v163, v179
	ds_write_b32 v91, v114 offset:17136
	v_mov_b32_e32 v82, v163
	v_mov_b32_e32 v83, v179
	v_or_b32_e32 v82, s0, v90
	v_mov_b64_e32 v[20:21], s[42:43]
	v_mad_u64_u32 v[20:21], s[4:5], v82, s45, v[20:21]
	s_mul_i32 s0, s1, 0xa00
	v_add_u32_e32 v21, s0, v21
	v_readlane_b32 s0, v252, 1
	s_lshl_b32 s94, s0, 1
	v_lshl_add_u64 v[20:21], v[20:21], 0, s[94:95]
	v_lshl_add_u64 v[20:21], v[50:51], 1, v[20:21]
	global_load_dwordx2 v[94:95], v[20:21], off offset:1536
	v_add_co_u32_e32 v22, vcc, s28, v20
	ds_read_b128 v[24:27], v92 offset:64
	s_nop 0
	v_addc_co_u32_e32 v23, vcc, 0, v21, vcc
	global_load_dwordx2 v[88:89], v[22:23], off offset:1536
	v_add_co_u32_e32 v22, vcc, s92, v20
	v_mov_b32_e32 v83, s1
	s_nop 0
	v_addc_co_u32_e32 v23, vcc, 0, v21, vcc
	v_add_co_u32_e32 v20, vcc, s49, v20
	global_load_dwordx2 v[86:87], v[22:23], off offset:1536
	s_nop 0
	v_addc_co_u32_e32 v21, vcc, 0, v21, vcc
	global_load_dwordx2 v[84:85], v[20:21], off offset:1536
	ds_read_b128 v[20:23], v92
	s_waitcnt lgkmcnt(0)
	v_mfma_f32_16x16x32_bf16 v[20:23], v[0:3], v[20:23], 0
	v_lshlrev_b64 v[82:83], 10, v[82:83]
	v_readlane_b32 s0, v251, 20
	s_add_i32 s2, s2, s0
	v_mfma_f32_16x16x32_bf16 v[20:23], v[4:7], v[24:27], v[20:23]
	ds_read_b128 v[24:27], v92 offset:128
	s_cmpk_gt_i32 s2, 0x3fff
	v_readlane_b32 s1, v251, 21
	s_waitcnt lgkmcnt(0)
	v_mfma_f32_16x16x32_bf16 v[20:23], v[8:11], v[24:27], v[20:23]
	ds_read_b128 v[24:27], v92 offset:192
	s_waitcnt lgkmcnt(0)
	v_mfma_f32_16x16x32_bf16 v[20:23], v[12:15], v[24:27], v[20:23]
	s_waitcnt vmcnt(3)
; __device__ __forceinline__ float gelu_tanh(float x) {
;   float u = 0.7978845608028654f * (x + 0.044715f * x * x * x);
;   float e = __expf(2.f * u);
;   float th = 1.f - 2.f * __builtin_amdgcn_rcpf(1.f + e);
;   return 0.5f * x * (1.f + th);
; }
; template <bool FINAL>
; __device__ __forceinline__ void s5_wave(const Params& P, int j, int g, int idx0, int stride, char* ldsw) {
;     ...
; #pragma unroll
;     for (int mt = 0; mt < 4; ++mt) {
;       f32x4 y = {0.f, 0.f, 0.f, 0.f};
; #pragma unroll
;       for (int ks = 0; ks < 4; ++ks) {
;         bf16x8 a = *reinterpret_cast<const bf16x8*>(hbuf + (mt * 16 + fr) * 68 + ks * 16 + fq * 4);
;         y = __builtin_amdgcn_mfma_f32_16x16x32_bf16(bc[ks], a, y, 0, 0, 0);
;       }
;       const float uvf[4] = {__uint_as_float(uw[mt].x << 16), __uint_as_float(uw[mt].x & 0xffff0000u),
;                             __uint_as_float(uw[mt].y << 16), __uint_as_float(uw[mt].y & 0xffff0000u)};
;       f32x4 zo;
; #pragma unroll
;       for (int i = 0; i < 4; ++i) zo[i] = gelu_tanh(y[i] + dv4[i] * uvf[i]);
;       *reinterpret_cast<uint2*>(zs + (rowbase + mt * 16 + fr) * 512 + g * 16 + 4 * fq) = pack4(zo);
;     }
	v_lshlrev_b32_e32 v24, 16, v94
	s_nop 5
	v_fma_f32 v20, v16, v24, v20
	v_mul_f32_e32 v24, 0x3d372713, v20
	v_mul_f32_e32 v24, v20, v24
	v_fma_f32 v24, v20, v24, v20
	v_mul_f32_e32 v24, 0x3f4c422a, v24
	v_add_f32_e32 v24, v24, v24
	v_mul_f32_e32 v24, 0x3fb8aa3b, v24
	v_exp_f32_e32 v24, v24
	v_and_b32_e32 v25, 0xffff0000, v94
	v_mul_f32_e32 v20, 0.5, v20
	v_fma_f32 v21, v17, v25, v21
	v_add_f32_e32 v24, 1.0, v24
	v_rcp_f32_e32 v24, v24
	v_lshlrev_b32_e32 v26, 16, v95
	v_fma_f32 v22, v18, v26, v22
	v_and_b32_e32 v27, 0xffff0000, v95
	v_fma_f32 v24, v24, -2.0, 1.0
	v_add_f32_e32 v24, 1.0, v24
	v_mul_f32_e32 v20, v20, v24
	v_mul_f32_e32 v24, 0x3d372713, v21
	v_mul_f32_e32 v24, v21, v24
	v_fma_f32 v24, v21, v24, v21
	v_mul_f32_e32 v24, 0x3f4c422a, v24
	v_add_f32_e32 v24, v24, v24
	v_mul_f32_e32 v24, 0x3fb8aa3b, v24
	v_exp_f32_e32 v24, v24
	v_mul_f32_e32 v21, 0.5, v21
	v_fmac_f32_e32 v23, v19, v27
	v_add_f32_e32 v24, 1.0, v24
	v_rcp_f32_e32 v24, v24
	s_nop 0
	v_fma_f32 v24, v24, -2.0, 1.0
	v_add_f32_e32 v24, 1.0, v24
	v_mul_f32_e32 v21, v21, v24
	v_mul_f32_e32 v24, 0x3d372713, v22
	v_mul_f32_e32 v24, v22, v24
	v_fma_f32 v24, v22, v24, v22
	v_mul_f32_e32 v24, 0x3f4c422a, v24
	v_add_f32_e32 v24, v24, v24
	v_mul_f32_e32 v24, 0x3fb8aa3b, v24
	v_exp_f32_e32 v24, v24
	v_mul_f32_e32 v22, 0.5, v22
	v_cvt_pk_bf16_f32 v20, v20, v21
	v_add_f32_e32 v24, 1.0, v24
	v_rcp_f32_e32 v24, v24
	s_nop 0
	v_fma_f32 v24, v24, -2.0, 1.0
	v_add_f32_e32 v24, 1.0, v24
	v_mul_f32_e32 v22, v22, v24
	v_mul_f32_e32 v24, 0x3d372713, v23
	v_mul_f32_e32 v24, v23, v24
	v_fma_f32 v24, v23, v24, v23
	v_mul_f32_e32 v24, 0x3f4c422a, v24
	v_add_f32_e32 v24, v24, v24
	v_mul_f32_e32 v24, 0x3fb8aa3b, v24
	v_exp_f32_e32 v24, v24
	v_mul_f32_e32 v23, 0.5, v23
	v_add_f32_e32 v24, 1.0, v24
	v_rcp_f32_e32 v24, v24
	s_nop 0
	v_fma_f32 v24, v24, -2.0, 1.0
	v_add_f32_e32 v24, 1.0, v24
	v_mul_f32_e32 v23, v23, v24
	v_cvt_pk_bf16_f32 v21, v22, v23
	v_lshl_add_u64 v[22:23], v[70:71], 0, v[82:83]
	global_store_dwordx2 v[22:23], v[20:21], off
	ds_read_b128 v[20:23], v92 offset:4352
	ds_read_b128 v[24:27], v92 offset:4416
	s_waitcnt lgkmcnt(1)
	v_mfma_f32_16x16x32_bf16 v[20:23], v[0:3], v[20:23], 0
	s_waitcnt lgkmcnt(0)
	v_mfma_f32_16x16x32_bf16 v[20:23], v[4:7], v[24:27], v[20:23]
	ds_read_b128 v[24:27], v92 offset:4480
	s_waitcnt lgkmcnt(0)
	v_mfma_f32_16x16x32_bf16 v[20:23], v[8:11], v[24:27], v[20:23]
	ds_read_b128 v[24:27], v92 offset:4544
	s_waitcnt lgkmcnt(0)
	v_mfma_f32_16x16x32_bf16 v[20:23], v[12:15], v[24:27], v[20:23]
	s_waitcnt vmcnt(3)
	v_lshlrev_b32_e32 v24, 16, v88
	v_and_b32_e32 v25, 0xffff0000, v88
	v_lshlrev_b32_e32 v26, 16, v89
	s_nop 3
	v_fma_f32 v20, v16, v24, v20
	v_mul_f32_e32 v24, 0x3d372713, v20
	v_mul_f32_e32 v24, v20, v24
	v_fma_f32 v24, v20, v24, v20
	v_mul_f32_e32 v24, 0x3f4c422a, v24
	v_add_f32_e32 v24, v24, v24
	v_mul_f32_e32 v24, 0x3fb8aa3b, v24
	v_exp_f32_e32 v24, v24
	v_mul_f32_e32 v20, 0.5, v20
	v_fma_f32 v21, v17, v25, v21
	v_fma_f32 v22, v18, v26, v22
	v_add_f32_e32 v24, 1.0, v24
	v_rcp_f32_e32 v24, v24
	v_and_b32_e32 v27, 0xffff0000, v89
	v_fmac_f32_e32 v23, v19, v27
	v_fma_f32 v24, v24, -2.0, 1.0
	v_add_f32_e32 v24, 1.0, v24
	v_mul_f32_e32 v20, v20, v24
	v_mul_f32_e32 v24, 0x3d372713, v21
	v_mul_f32_e32 v24, v21, v24
	v_fma_f32 v24, v21, v24, v21
	v_mul_f32_e32 v24, 0x3f4c422a, v24
	v_add_f32_e32 v24, v24, v24
	v_mul_f32_e32 v24, 0x3fb8aa3b, v24
	v_exp_f32_e32 v24, v24
	v_mul_f32_e32 v21, 0.5, v21
	v_add_f32_e32 v24, 1.0, v24
	v_rcp_f32_e32 v24, v24
	s_nop 0
	v_fma_f32 v24, v24, -2.0, 1.0
	v_add_f32_e32 v24, 1.0, v24
	v_mul_f32_e32 v21, v21, v24
	v_mul_f32_e32 v24, 0x3d372713, v22
	v_mul_f32_e32 v24, v22, v24
	v_fma_f32 v24, v22, v24, v22
	v_mul_f32_e32 v24, 0x3f4c422a, v24
	v_add_f32_e32 v24, v24, v24
	v_mul_f32_e32 v24, 0x3fb8aa3b, v24
	v_exp_f32_e32 v24, v24
	v_mul_f32_e32 v22, 0.5, v22
	v_cvt_pk_bf16_f32 v20, v20, v21
	v_add_f32_e32 v24, 1.0, v24
	v_rcp_f32_e32 v24, v24
	s_nop 0
	v_fma_f32 v24, v24, -2.0, 1.0
	v_add_f32_e32 v24, 1.0, v24
	v_mul_f32_e32 v22, v22, v24
	v_mul_f32_e32 v24, 0x3d372713, v23
	v_mul_f32_e32 v24, v23, v24
	v_fma_f32 v24, v23, v24, v23
	v_mul_f32_e32 v24, 0x3f4c422a, v24
	v_add_f32_e32 v24, v24, v24
	v_mul_f32_e32 v24, 0x3fb8aa3b, v24
	v_exp_f32_e32 v24, v24
	v_mul_f32_e32 v23, 0.5, v23
	v_add_f32_e32 v24, 1.0, v24
	v_rcp_f32_e32 v24, v24
	s_nop 0
	v_fma_f32 v24, v24, -2.0, 1.0
	v_add_f32_e32 v24, 1.0, v24
	v_mul_f32_e32 v23, v23, v24
	v_cvt_pk_bf16_f32 v21, v22, v23
	v_or_b32_e32 v22, 0x4000, v82
	v_mov_b32_e32 v23, v83
	v_lshl_add_u64 v[22:23], v[70:71], 0, v[22:23]
	global_store_dwordx2 v[22:23], v[20:21], off
	ds_read_b128 v[20:23], v92 offset:8704
	ds_read_b128 v[24:27], v92 offset:8768
	s_waitcnt lgkmcnt(1)
	v_mfma_f32_16x16x32_bf16 v[20:23], v[0:3], v[20:23], 0
	s_waitcnt lgkmcnt(0)
	v_mfma_f32_16x16x32_bf16 v[20:23], v[4:7], v[24:27], v[20:23]
	ds_read_b128 v[24:27], v92 offset:8832
	s_waitcnt lgkmcnt(0)
; template <bool FINAL>
; __device__ __forceinline__ void s5_wave(const Params& P, int j, int g, int idx0, int stride, char* ldsw) {
;     ...
; #pragma unroll
;     for (int mt = 0; mt < 4; ++mt) {
;       f32x4 y = {0.f, 0.f, 0.f, 0.f};
; #pragma unroll
;       for (int ks = 0; ks < 4; ++ks) {
;         bf16x8 a = *reinterpret_cast<const bf16x8*>(hbuf + (mt * 16 + fr) * 68 + ks * 16 + fq * 4);
;         y = __builtin_amdgcn_mfma_f32_16x16x32_bf16(bc[ks], a, y, 0, 0, 0);
;       }
;       const float uvf[4] = {__uint_as_float(uw[mt].x << 16), __uint_as_float(uw[mt].x & 0xffff0000u),
;                             __uint_as_float(uw[mt].y << 16), __uint_as_float(uw[mt].y & 0xffff0000u)};
;       f32x4 zo;
; #pragma unroll
;       for (int i = 0; i < 4; ++i) zo[i] = gelu_tanh(y[i] + dv4[i] * uvf[i]);
;       *reinterpret_cast<uint2*>(zs + (rowbase + mt * 16 + fr) * 512 + g * 16 + 4 * fq) = pack4(zo);
;     }
	v_mfma_f32_16x16x32_bf16 v[20:23], v[8:11], v[24:27], v[20:23]
	ds_read_b128 v[24:27], v92 offset:8896
	s_waitcnt lgkmcnt(0)
	v_mfma_f32_16x16x32_bf16 v[20:23], v[12:15], v[24:27], v[20:23]
	s_waitcnt vmcnt(3)
	v_lshlrev_b32_e32 v24, 16, v86
	v_and_b32_e32 v25, 0xffff0000, v86
	v_lshlrev_b32_e32 v26, 16, v87
	s_nop 3
	v_fma_f32 v20, v16, v24, v20
	v_mul_f32_e32 v24, 0x3d372713, v20
	v_mul_f32_e32 v24, v20, v24
	v_fma_f32 v24, v20, v24, v20
	v_mul_f32_e32 v24, 0x3f4c422a, v24
	v_add_f32_e32 v24, v24, v24
	v_mul_f32_e32 v24, 0x3fb8aa3b, v24
	v_exp_f32_e32 v24, v24
	v_mul_f32_e32 v20, 0.5, v20
	v_fma_f32 v21, v17, v25, v21
	v_fma_f32 v22, v18, v26, v22
	v_add_f32_e32 v24, 1.0, v24
	v_rcp_f32_e32 v24, v24
	v_and_b32_e32 v27, 0xffff0000, v87
	v_fmac_f32_e32 v23, v19, v27
	v_fma_f32 v24, v24, -2.0, 1.0
	v_add_f32_e32 v24, 1.0, v24
	v_mul_f32_e32 v20, v20, v24
	v_mul_f32_e32 v24, 0x3d372713, v21
	v_mul_f32_e32 v24, v21, v24
	v_fma_f32 v24, v21, v24, v21
	v_mul_f32_e32 v24, 0x3f4c422a, v24
	v_add_f32_e32 v24, v24, v24
	v_mul_f32_e32 v24, 0x3fb8aa3b, v24
	v_exp_f32_e32 v24, v24
	v_mul_f32_e32 v21, 0.5, v21
	v_add_f32_e32 v24, 1.0, v24
	v_rcp_f32_e32 v24, v24
	s_nop 0
	v_fma_f32 v24, v24, -2.0, 1.0
	v_add_f32_e32 v24, 1.0, v24
	v_mul_f32_e32 v21, v21, v24
	v_mul_f32_e32 v24, 0x3d372713, v22
	v_mul_f32_e32 v24, v22, v24
	v_fma_f32 v24, v22, v24, v22
	v_mul_f32_e32 v24, 0x3f4c422a, v24
	v_add_f32_e32 v24, v24, v24
	v_mul_f32_e32 v24, 0x3fb8aa3b, v24
	v_exp_f32_e32 v24, v24
	v_mul_f32_e32 v22, 0.5, v22
	v_cvt_pk_bf16_f32 v20, v20, v21
	v_add_f32_e32 v24, 1.0, v24
	v_rcp_f32_e32 v24, v24
	s_nop 0
	v_fma_f32 v24, v24, -2.0, 1.0
	v_add_f32_e32 v24, 1.0, v24
	v_mul_f32_e32 v22, v22, v24
	v_mul_f32_e32 v24, 0x3d372713, v23
	v_mul_f32_e32 v24, v23, v24
	v_fma_f32 v24, v23, v24, v23
	v_mul_f32_e32 v24, 0x3f4c422a, v24
	v_add_f32_e32 v24, v24, v24
	v_mul_f32_e32 v24, 0x3fb8aa3b, v24
	v_exp_f32_e32 v24, v24
	v_mul_f32_e32 v23, 0.5, v23
	v_add_f32_e32 v24, 1.0, v24
	v_rcp_f32_e32 v24, v24
	s_nop 0
	v_fma_f32 v24, v24, -2.0, 1.0
	v_add_f32_e32 v24, 1.0, v24
	v_mul_f32_e32 v23, v23, v24
	v_cvt_pk_bf16_f32 v21, v22, v23
	v_or_b32_e32 v22, 0x8000, v82
	v_mov_b32_e32 v23, v83
	v_lshl_add_u64 v[22:23], v[70:71], 0, v[22:23]
	global_store_dwordx2 v[22:23], v[20:21], off
	ds_read_b128 v[20:23], v92 offset:13056
	ds_read_b128 v[24:27], v92 offset:13120
	s_waitcnt lgkmcnt(1)
	v_mfma_f32_16x16x32_bf16 v[20:23], v[0:3], v[20:23], 0
	v_or_b32_e32 v82, 0xc000, v82
	s_waitcnt lgkmcnt(0)
	v_mfma_f32_16x16x32_bf16 v[20:23], v[4:7], v[24:27], v[20:23]
	ds_read_b128 v[24:27], v92 offset:13184
	s_waitcnt lgkmcnt(0)
	v_mfma_f32_16x16x32_bf16 v[20:23], v[8:11], v[24:27], v[20:23]
	ds_read_b128 v[24:27], v92 offset:13248
	s_waitcnt lgkmcnt(0)
	v_mfma_f32_16x16x32_bf16 v[20:23], v[12:15], v[24:27], v[20:23]
	s_waitcnt vmcnt(3)
	v_lshlrev_b32_e32 v24, 16, v84
	v_and_b32_e32 v25, 0xffff0000, v84
	v_lshlrev_b32_e32 v26, 16, v85
	s_nop 3
	v_fma_f32 v20, v16, v24, v20
	v_mul_f32_e32 v24, 0x3d372713, v20
	v_mul_f32_e32 v24, v20, v24
	v_fma_f32 v24, v20, v24, v20
	v_mul_f32_e32 v24, 0x3f4c422a, v24
	v_add_f32_e32 v24, v24, v24
	v_mul_f32_e32 v24, 0x3fb8aa3b, v24
	v_exp_f32_e32 v24, v24
	v_mul_f32_e32 v20, 0.5, v20
	v_fma_f32 v21, v17, v25, v21
	v_fma_f32 v22, v18, v26, v22
	v_add_f32_e32 v24, 1.0, v24
	v_rcp_f32_e32 v24, v24
	v_and_b32_e32 v27, 0xffff0000, v85
	v_fmac_f32_e32 v23, v19, v27
	v_fma_f32 v24, v24, -2.0, 1.0
	v_add_f32_e32 v24, 1.0, v24
	v_mul_f32_e32 v20, v20, v24
	v_mul_f32_e32 v24, 0x3d372713, v21
	v_mul_f32_e32 v24, v21, v24
	v_fma_f32 v24, v21, v24, v21
	v_mul_f32_e32 v24, 0x3f4c422a, v24
	v_add_f32_e32 v24, v24, v24
	v_mul_f32_e32 v24, 0x3fb8aa3b, v24
	v_exp_f32_e32 v24, v24
	v_mul_f32_e32 v21, 0.5, v21
	v_add_f32_e32 v24, 1.0, v24
	v_rcp_f32_e32 v24, v24
	s_nop 0
	v_fma_f32 v24, v24, -2.0, 1.0
	v_add_f32_e32 v24, 1.0, v24
	v_mul_f32_e32 v21, v21, v24
	v_mul_f32_e32 v24, 0x3d372713, v22
	v_mul_f32_e32 v24, v22, v24
	v_fma_f32 v24, v22, v24, v22
	v_mul_f32_e32 v24, 0x3f4c422a, v24
	v_add_f32_e32 v24, v24, v24
	v_mul_f32_e32 v24, 0x3fb8aa3b, v24
	v_exp_f32_e32 v24, v24
	v_mul_f32_e32 v22, 0.5, v22
	v_cvt_pk_bf16_f32 v20, v20, v21
	v_add_f32_e32 v24, 1.0, v24
	v_rcp_f32_e32 v24, v24
	s_nop 0
	v_fma_f32 v24, v24, -2.0, 1.0
	v_add_f32_e32 v24, 1.0, v24
	v_mul_f32_e32 v22, v22, v24
	v_mul_f32_e32 v24, 0x3d372713, v23
	v_mul_f32_e32 v24, v23, v24
	v_fma_f32 v24, v23, v24, v23
	v_mul_f32_e32 v24, 0x3f4c422a, v24
	v_add_f32_e32 v24, v24, v24
	v_mul_f32_e32 v24, 0x3fb8aa3b, v24
	v_exp_f32_e32 v24, v24
	v_mul_f32_e32 v23, 0.5, v23
	v_add_f32_e32 v24, 1.0, v24
	v_rcp_f32_e32 v24, v24
	s_nop 0
	v_fma_f32 v24, v24, -2.0, 1.0
	v_add_f32_e32 v24, 1.0, v24
	v_mul_f32_e32 v23, v23, v24
	v_cvt_pk_bf16_f32 v21, v22, v23
	v_lshl_add_u64 v[22:23], v[70:71], 0, v[82:83]
	global_store_dwordx2 v[22:23], v[20:21], off
	s_cbranch_scc0 .LBB0_430

; template <bool FINAL>
; __device__ __forceinline__ void s5_wave(const Params& P, int j, int g, int idx0, int stride, char* ldsw) {
;     ...
;   for (int idx = idx0; idx < 16384; idx += stride) {
;   const int b = idx >> 11, chunk = ((idx >> 5) + 8 * b) & 63;
;   const size_t rowbase = (size_t)b * 4096 + chunk * 64;
;   const u16* up = Zo + (rowbase + lane) * 1280 + 768 + g * 16;
;   const uint4 u0 = *reinterpret_cast<const uint4*>(up);
;   const uint4 u1 = *reinterpret_cast<const uint4*>(up + 8);
;     ...
;   for (int t = 0; t < 64; ++t) {
;     uint32_t w[8];
;     w[0] = __builtin_amdgcn_readlane(u0.x, t); w[1] = __builtin_amdgcn_readlane(u0.y, t);
;     w[2] = __builtin_amdgcn_readlane(u0.z, t); w[3] = __builtin_amdgcn_readlane(u0.w, t);
;     w[4] = __builtin_amdgcn_readlane(u1.x, t); w[5] = __builtin_amdgcn_readlane(u1.y, t);
;     w[6] = __builtin_amdgcn_readlane(u1.z, t); w[7] = __builtin_amdgcn_readlane(u1.w, t);
;     f32x2 acc0 = (f32x2){lbr * hr - lbi * hi, lbr * hi + lbi * hr}, acc1 = (f32x2){0.f, 0.f};
; #pragma unroll
;     for (int q = 0; q < 8; ++q) {
;       float ua = __uint_as_float(w[q] << 16), ub = __uint_as_float(w[q] & 0xffff0000u);
;       acc0 = bb[2 * q] * (f32x2){ua, ua} + acc0;
;       acc1 = bb[2 * q + 1] * (f32x2){ub, ub} + acc1;
;     }
;     acc0 = acc0 + acc1;
;     hr = acc0.x; hi = acc0.y;
.Ls5p1_job:
	s_ashr_i32 s0, s2, 11
	s_lshr_b32 s1, s2, 5
	s_lshl_b32 s4, s0, 3
	s_add_i32 s4, s4, s1
	s_and_b32 s4, s4, 63
	s_lshl_b32 s6, s0, 12
	s_lshl_b32 s7, s4, 6
	s_or_b32 s6, s6, s7
	s_mul_i32 s6, s6, 0xa00
	s_add_u32 s6, s6, s5
	s_add_u32 s8, s90, s6
	s_addc_u32 s9, s91, 0
	s_add_u32 s10, s8, 0x14000
	s_addc_u32 s11, s9, 0
	v_lshl_add_u64 v[64:65], v[110:111], 0, s[10:11]
	global_load_dwordx4 v[56:59], v[64:65], off
	global_load_dwordx4 v[60:63], v[64:65], off offset:16
	s_lshl_b32 s14, s0, 6
	s_or_b32 s14, s4, s14
	s_ashr_i32 s15, s14, 31
	s_lshl_b64 s[14:15], s[14:15], 14
	v_lshl_add_u64 v[66:67], v[44:45], 0, s[14:15]
	v_readlane_b32 s17, v251, 20
	s_add_i32 s17, s2, s17
	s_cmpk_gt_i32 s17, 0x3fff
	s_cselect_b32 s17, s2, s17
	s_ashr_i32 s0, s17, 11
	s_lshr_b32 s1, s17, 5
	s_lshl_b32 s4, s0, 3
	s_add_i32 s4, s4, s1
	s_and_b32 s4, s4, 63
	s_lshl_b32 s6, s0, 12
	s_lshl_b32 s7, s4, 6
	s_or_b32 s6, s6, s7
	s_mul_i32 s6, s6, 0xa00
	s_add_u32 s6, s6, s5
	s_add_u32 s10, s90, s6
	s_addc_u32 s11, s91, 0
	v_mov_b32_e32 v54, 0
	v_mov_b32_e32 v55, 0
	s_waitcnt vmcnt(3)
	v_lshlrev_b32_e32 v100, v108, v0
	v_lshlrev_b32_e32 v101, v108, v1
	v_lshlrev_b32_e32 v102, v108, v2
	v_lshlrev_b32_e32 v103, v108, v3
	v_lshlrev_b32_e32 v104, v108, v4
	v_lshlrev_b32_e32 v105, v108, v5
	v_lshlrev_b32_e32 v106, v108, v6
	v_lshlrev_b32_e32 v107, v108, v7
	v_and_b32_e32 v100, 0xffff0000, v100
	v_and_b32_e32 v101, 0xffff0000, v101
	v_and_b32_e32 v102, 0xffff0000, v102
	v_and_b32_e32 v103, 0xffff0000, v103
	v_and_b32_e32 v104, 0xffff0000, v104
	v_and_b32_e32 v105, 0xffff0000, v105
	v_and_b32_e32 v106, 0xffff0000, v106
	v_and_b32_e32 v107, 0xffff0000, v107
	v_lshl_add_u64 v[64:65], v[110:111], 0, s[10:11]
	global_load_dwordx4 v[0:3], v[64:65], off
	global_load_dwordx4 v[4:7], v[64:65], off offset:16
	s_setprio 1
	v_mfma_f32_32x32x2_f32 v[116:131], v100, v36, 0
	v_mfma_f32_32x32x2_f32 v[132:147], v100, v37, 0
	v_mfma_f32_32x32x2_f32 v[148:163], v100, v28, 0
	v_mfma_f32_32x32x2_f32 v[164:179], v100, v29, 0
	v_mfma_f32_32x32x2_f32 v[116:131], v101, v24, v[116:131]
	v_mfma_f32_32x32x2_f32 v[132:147], v101, v25, v[132:147]
	v_mfma_f32_32x32x2_f32 v[148:163], v101, v26, v[148:163]
	v_mfma_f32_32x32x2_f32 v[164:179], v101, v27, v[164:179]
	v_mfma_f32_32x32x2_f32 v[116:131], v102, v30, v[116:131]
	v_mfma_f32_32x32x2_f32 v[132:147], v102, v31, v[132:147]
	v_mfma_f32_32x32x2_f32 v[148:163], v102, v20, v[148:163]
	v_mfma_f32_32x32x2_f32 v[164:179], v102, v21, v[164:179]
	v_mfma_f32_32x32x2_f32 v[116:131], v103, v16, v[116:131]
	v_mfma_f32_32x32x2_f32 v[132:147], v103, v17, v[132:147]
	v_mfma_f32_32x32x2_f32 v[148:163], v103, v18, v[148:163]
	v_mfma_f32_32x32x2_f32 v[164:179], v103, v19, v[164:179]
	v_mfma_f32_32x32x2_f32 v[116:131], v104, v22, v[116:131]
	v_mfma_f32_32x32x2_f32 v[132:147], v104, v23, v[132:147]
	v_mfma_f32_32x32x2_f32 v[148:163], v104, v12, v[148:163]
	v_mfma_f32_32x32x2_f32 v[164:179], v104, v13, v[164:179]
	v_mfma_f32_32x32x2_f32 v[116:131], v105, v8, v[116:131]
	v_mfma_f32_32x32x2_f32 v[132:147], v105, v9, v[132:147]
	v_mfma_f32_32x32x2_f32 v[148:163], v105, v10, v[148:163]
	v_mfma_f32_32x32x2_f32 v[164:179], v105, v11, v[164:179]
	v_mfma_f32_32x32x2_f32 v[116:131], v106, v14, v[116:131]
	v_mfma_f32_32x32x2_f32 v[132:147], v106, v15, v[132:147]
	v_mfma_f32_32x32x2_f32 v[148:163], v106, v38, v[148:163]
	v_mfma_f32_32x32x2_f32 v[164:179], v106, v39, v[164:179]
	v_mfma_f32_32x32x2_f32 v[116:131], v107, v40, v[116:131]
	v_mfma_f32_32x32x2_f32 v[132:147], v107, v41, v[132:147]
	v_mfma_f32_32x32x2_f32 v[148:163], v107, v42, v[148:163]
	v_mfma_f32_32x32x2_f32 v[164:179], v107, v43, v[164:179]
	s_setprio 0
	s_nop 15
	s_nop 3
	v_permlane32_swap_b32_e32 v116, v148
	v_permlane32_swap_b32_e32 v132, v164
	v_permlane32_swap_b32_e32 v117, v149
	v_permlane32_swap_b32_e32 v133, v165
	v_permlane32_swap_b32_e32 v118, v150
	v_permlane32_swap_b32_e32 v134, v166
	v_permlane32_swap_b32_e32 v119, v151
	v_permlane32_swap_b32_e32 v135, v167
	v_permlane32_swap_b32_e32 v120, v152
	v_permlane32_swap_b32_e32 v136, v168
	v_permlane32_swap_b32_e32 v121, v153
	v_permlane32_swap_b32_e32 v137, v169
	v_permlane32_swap_b32_e32 v122, v154
	v_permlane32_swap_b32_e32 v138, v170
	v_permlane32_swap_b32_e32 v123, v155
	v_permlane32_swap_b32_e32 v139, v171
	v_permlane32_swap_b32_e32 v124, v156
	v_permlane32_swap_b32_e32 v140, v172
	v_permlane32_swap_b32_e32 v125, v157
	v_permlane32_swap_b32_e32 v141, v173
	v_permlane32_swap_b32_e32 v126, v158
	v_permlane32_swap_b32_e32 v142, v174
	v_permlane32_swap_b32_e32 v127, v159
	v_permlane32_swap_b32_e32 v143, v175
	v_permlane32_swap_b32_e32 v128, v160
	v_permlane32_swap_b32_e32 v144, v176
	v_permlane32_swap_b32_e32 v129, v161
	v_permlane32_swap_b32_e32 v145, v177
	v_permlane32_swap_b32_e32 v130, v162
	v_permlane32_swap_b32_e32 v146, v178
	v_permlane32_swap_b32_e32 v131, v163
	v_permlane32_swap_b32_e32 v147, v179
	v_fma_f32 v116, v34, v54, v116
	v_fma_f32 v132, v34, v55, v132
	v_fma_f32 v116, -v35, v55, v116
	v_fma_f32 v132, v35, v54, v132
	v_fma_f32 v117, v34, v116, v117
	v_fma_f32 v133, v34, v132, v133
	v_fma_f32 v117, -v35, v132, v117
	v_fma_f32 v133, v35, v116, v133
	v_fma_f32 v118, v34, v117, v118
	v_fma_f32 v134, v34, v133, v134
	v_fma_f32 v118, -v35, v133, v118
	v_fma_f32 v134, v35, v117, v134
	v_fma_f32 v119, v34, v118, v119
	v_fma_f32 v135, v34, v134, v135
	v_fma_f32 v119, -v35, v134, v119
	v_fma_f32 v135, v35, v118, v135
	v_fma_f32 v148, v34, v119, v148
	v_fma_f32 v164, v34, v135, v164
	v_fma_f32 v148, -v35, v135, v148
	v_fma_f32 v164, v35, v119, v164
	v_fma_f32 v149, v34, v148, v149
	v_fma_f32 v165, v34, v164, v165
	v_fma_f32 v149, -v35, v164, v149
; template <bool FINAL>
; __device__ __forceinline__ void s5_wave(const Params& P, int j, int g, int idx0, int stride, char* ldsw) {
;     ...
;   for (int t = 0; t < 64; ++t) {
;     uint32_t w[8];
;     w[0] = __builtin_amdgcn_readlane(u0.x, t); w[1] = __builtin_amdgcn_readlane(u0.y, t);
;     w[2] = __builtin_amdgcn_readlane(u0.z, t); w[3] = __builtin_amdgcn_readlane(u0.w, t);
;     w[4] = __builtin_amdgcn_readlane(u1.x, t); w[5] = __builtin_amdgcn_readlane(u1.y, t);
;     w[6] = __builtin_amdgcn_readlane(u1.z, t); w[7] = __builtin_amdgcn_readlane(u1.w, t);
;     f32x2 acc0 = (f32x2){lbr * hr - lbi * hi, lbr * hi + lbi * hr}, acc1 = (f32x2){0.f, 0.f};
; #pragma unroll
;     for (int q = 0; q < 8; ++q) {
;       float ua = __uint_as_float(w[q] << 16), ub = __uint_as_float(w[q] & 0xffff0000u);
;       acc0 = bb[2 * q] * (f32x2){ua, ua} + acc0;
;       acc1 = bb[2 * q + 1] * (f32x2){ub, ub} + acc1;
;     }
;     acc0 = acc0 + acc1;
;     hr = acc0.x; hi = acc0.y;
	v_fma_f32 v165, v35, v148, v165
	v_fma_f32 v150, v34, v149, v150
	v_fma_f32 v166, v34, v165, v166
	v_fma_f32 v150, -v35, v165, v150
	v_fma_f32 v166, v35, v149, v166
	v_fma_f32 v151, v34, v150, v151
	v_fma_f32 v167, v34, v166, v167
	v_fma_f32 v151, -v35, v166, v151
	v_fma_f32 v167, v35, v150, v167
	v_fma_f32 v120, v34, v151, v120
	v_fma_f32 v136, v34, v167, v136
	v_fma_f32 v120, -v35, v167, v120
	v_fma_f32 v136, v35, v151, v136
	v_fma_f32 v121, v34, v120, v121
	v_fma_f32 v137, v34, v136, v137
	v_fma_f32 v121, -v35, v136, v121
	v_fma_f32 v137, v35, v120, v137
	v_fma_f32 v122, v34, v121, v122
	v_fma_f32 v138, v34, v137, v138
	v_fma_f32 v122, -v35, v137, v122
	v_fma_f32 v138, v35, v121, v138
	v_fma_f32 v123, v34, v122, v123
	v_fma_f32 v139, v34, v138, v139
	v_fma_f32 v123, -v35, v138, v123
	v_fma_f32 v139, v35, v122, v139
	v_fma_f32 v152, v34, v123, v152
	v_fma_f32 v168, v34, v139, v168
	v_fma_f32 v152, -v35, v139, v152
	v_fma_f32 v168, v35, v123, v168
	v_fma_f32 v153, v34, v152, v153
	v_fma_f32 v169, v34, v168, v169
	v_fma_f32 v153, -v35, v168, v153
	v_fma_f32 v169, v35, v152, v169
	v_fma_f32 v154, v34, v153, v154
	v_fma_f32 v170, v34, v169, v170
	v_fma_f32 v154, -v35, v169, v154
	v_fma_f32 v170, v35, v153, v170
	v_fma_f32 v155, v34, v154, v155
	v_fma_f32 v171, v34, v170, v171
	v_fma_f32 v155, -v35, v170, v155
	v_fma_f32 v171, v35, v154, v171
	v_fma_f32 v124, v34, v155, v124
	v_fma_f32 v140, v34, v171, v140
	v_fma_f32 v124, -v35, v171, v124
	v_fma_f32 v140, v35, v155, v140
	v_fma_f32 v125, v34, v124, v125
	v_fma_f32 v141, v34, v140, v141
	v_fma_f32 v125, -v35, v140, v125
	v_fma_f32 v141, v35, v124, v141
	v_fma_f32 v126, v34, v125, v126
	v_fma_f32 v142, v34, v141, v142
	v_fma_f32 v126, -v35, v141, v126
	v_fma_f32 v142, v35, v125, v142
	v_fma_f32 v127, v34, v126, v127
	v_fma_f32 v143, v34, v142, v143
	v_fma_f32 v127, -v35, v142, v127
	v_fma_f32 v143, v35, v126, v143
	v_fma_f32 v156, v34, v127, v156
	v_fma_f32 v172, v34, v143, v172
	v_fma_f32 v156, -v35, v143, v156
	v_fma_f32 v172, v35, v127, v172
	v_fma_f32 v157, v34, v156, v157
	v_fma_f32 v173, v34, v172, v173
	v_fma_f32 v157, -v35, v172, v157
	v_fma_f32 v173, v35, v156, v173
	v_fma_f32 v158, v34, v157, v158
	v_fma_f32 v174, v34, v173, v174
	v_fma_f32 v158, -v35, v173, v158
	v_fma_f32 v174, v35, v157, v174
	v_fma_f32 v159, v34, v158, v159
	v_fma_f32 v175, v34, v174, v175
	v_fma_f32 v159, -v35, v174, v159
	v_fma_f32 v175, v35, v158, v175
	v_fma_f32 v128, v34, v159, v128
	v_fma_f32 v144, v34, v175, v144
	v_fma_f32 v128, -v35, v175, v128
	v_fma_f32 v144, v35, v159, v144
	v_fma_f32 v129, v34, v128, v129
	v_fma_f32 v145, v34, v144, v145
	v_fma_f32 v129, -v35, v144, v129
	v_fma_f32 v145, v35, v128, v145
	v_fma_f32 v130, v34, v129, v130
	v_fma_f32 v146, v34, v145, v146
	v_fma_f32 v130, -v35, v145, v130
	v_fma_f32 v146, v35, v129, v146
	v_fma_f32 v131, v34, v130, v131
	v_fma_f32 v147, v34, v146, v147
	v_fma_f32 v131, -v35, v146, v131
	v_fma_f32 v147, v35, v130, v147
	v_fma_f32 v160, v34, v131, v160
	v_fma_f32 v176, v34, v147, v176
	v_fma_f32 v160, -v35, v147, v160
	v_fma_f32 v176, v35, v131, v176
	v_fma_f32 v161, v34, v160, v161
	v_fma_f32 v177, v34, v176, v177
	v_fma_f32 v161, -v35, v176, v161
	v_fma_f32 v177, v35, v160, v177
	v_fma_f32 v162, v34, v161, v162
	v_fma_f32 v178, v34, v177, v178
	v_fma_f32 v162, -v35, v177, v162
	v_fma_f32 v178, v35, v161, v178
	v_fma_f32 v163, v34, v162, v163
	v_fma_f32 v179, v34, v178, v179
	v_fma_f32 v163, -v35, v178, v163
	v_fma_f32 v179, v35, v162, v179
	v_mov_b32_e32 v54, v163
	v_mov_b32_e32 v55, v179
	s_waitcnt vmcnt(2)
	v_lshlrev_b32_e32 v100, v108, v56
	v_lshlrev_b32_e32 v101, v108, v57
	v_lshlrev_b32_e32 v102, v108, v58
	v_lshlrev_b32_e32 v103, v108, v59
	v_lshlrev_b32_e32 v104, v108, v60
	v_lshlrev_b32_e32 v105, v108, v61
	v_lshlrev_b32_e32 v106, v108, v62
	v_lshlrev_b32_e32 v107, v108, v63
	v_and_b32_e32 v100, 0xffff0000, v100
	v_and_b32_e32 v101, 0xffff0000, v101
	v_and_b32_e32 v102, 0xffff0000, v102
	v_and_b32_e32 v103, 0xffff0000, v103
	v_and_b32_e32 v104, 0xffff0000, v104
	v_and_b32_e32 v105, 0xffff0000, v105
	v_and_b32_e32 v106, 0xffff0000, v106
	v_and_b32_e32 v107, 0xffff0000, v107
	s_setprio 1
	v_mfma_f32_32x32x2_f32 v[116:131], v100, v36, 0
	v_mfma_f32_32x32x2_f32 v[132:147], v100, v37, 0
	v_mfma_f32_32x32x2_f32 v[148:163], v100, v28, 0
	v_mfma_f32_32x32x2_f32 v[164:179], v100, v29, 0
	v_mfma_f32_32x32x2_f32 v[116:131], v101, v24, v[116:131]
	v_mfma_f32_32x32x2_f32 v[132:147], v101, v25, v[132:147]
	v_mfma_f32_32x32x2_f32 v[148:163], v101, v26, v[148:163]
	v_mfma_f32_32x32x2_f32 v[164:179], v101, v27, v[164:179]
	v_mfma_f32_32x32x2_f32 v[116:131], v102, v30, v[116:131]
	v_mfma_f32_32x32x2_f32 v[132:147], v102, v31, v[132:147]
	v_mfma_f32_32x32x2_f32 v[148:163], v102, v20, v[148:163]
	v_mfma_f32_32x32x2_f32 v[164:179], v102, v21, v[164:179]
	v_mfma_f32_32x32x2_f32 v[116:131], v103, v16, v[116:131]
	v_mfma_f32_32x32x2_f32 v[132:147], v103, v17, v[132:147]
	v_mfma_f32_32x32x2_f32 v[148:163], v103, v18, v[148:163]
	v_mfma_f32_32x32x2_f32 v[164:179], v103, v19, v[164:179]
	v_mfma_f32_32x32x2_f32 v[116:131], v104, v22, v[116:131]
	v_mfma_f32_32x32x2_f32 v[132:147], v104, v23, v[132:147]
	v_mfma_f32_32x32x2_f32 v[148:163], v104, v12, v[148:163]
	v_mfma_f32_32x32x2_f32 v[164:179], v104, v13, v[164:179]
	v_mfma_f32_32x32x2_f32 v[116:131], v105, v8, v[116:131]
	v_mfma_f32_32x32x2_f32 v[132:147], v105, v9, v[132:147]
	v_mfma_f32_32x32x2_f32 v[148:163], v105, v10, v[148:163]
	v_mfma_f32_32x32x2_f32 v[164:179], v105, v11, v[164:179]
	v_mfma_f32_32x32x2_f32 v[116:131], v106, v14, v[116:131]
	v_mfma_f32_32x32x2_f32 v[132:147], v106, v15, v[132:147]
; template <bool FINAL>
; __device__ __forceinline__ void s5_wave(const Params& P, int j, int g, int idx0, int stride, char* ldsw) {
;     ...
;   for (int t = 0; t < 64; ++t) {
;     uint32_t w[8];
;     w[0] = __builtin_amdgcn_readlane(u0.x, t); w[1] = __builtin_amdgcn_readlane(u0.y, t);
;     w[2] = __builtin_amdgcn_readlane(u0.z, t); w[3] = __builtin_amdgcn_readlane(u0.w, t);
;     w[4] = __builtin_amdgcn_readlane(u1.x, t); w[5] = __builtin_amdgcn_readlane(u1.y, t);
;     w[6] = __builtin_amdgcn_readlane(u1.z, t); w[7] = __builtin_amdgcn_readlane(u1.w, t);
;     f32x2 acc0 = (f32x2){lbr * hr - lbi * hi, lbr * hi + lbi * hr}, acc1 = (f32x2){0.f, 0.f};
; #pragma unroll
;     for (int q = 0; q < 8; ++q) {
;       float ua = __uint_as_float(w[q] << 16), ub = __uint_as_float(w[q] & 0xffff0000u);
;       acc0 = bb[2 * q] * (f32x2){ua, ua} + acc0;
;       acc1 = bb[2 * q + 1] * (f32x2){ub, ub} + acc1;
;     }
;     acc0 = acc0 + acc1;
;     hr = acc0.x; hi = acc0.y;
;     if (FINAL) hbuf[t * 68 + p] = pack2(hr, hi);
;   }
;   if (!FINAL) {
;     hend[((size_t)(b * 64 + chunk) * 32 + g) * 64 + p] = make_float2(hr, hi);
	v_mfma_f32_32x32x2_f32 v[148:163], v106, v38, v[148:163]
	v_mfma_f32_32x32x2_f32 v[164:179], v106, v39, v[164:179]
	v_mfma_f32_32x32x2_f32 v[116:131], v107, v40, v[116:131]
	v_mfma_f32_32x32x2_f32 v[132:147], v107, v41, v[132:147]
	v_mfma_f32_32x32x2_f32 v[148:163], v107, v42, v[148:163]
	v_mfma_f32_32x32x2_f32 v[164:179], v107, v43, v[164:179]
	s_setprio 0
	s_nop 15
	s_nop 3
	v_permlane32_swap_b32_e32 v116, v148
	v_permlane32_swap_b32_e32 v132, v164
	v_permlane32_swap_b32_e32 v117, v149
	v_permlane32_swap_b32_e32 v133, v165
	v_permlane32_swap_b32_e32 v118, v150
	v_permlane32_swap_b32_e32 v134, v166
	v_permlane32_swap_b32_e32 v119, v151
	v_permlane32_swap_b32_e32 v135, v167
	v_permlane32_swap_b32_e32 v120, v152
	v_permlane32_swap_b32_e32 v136, v168
	v_permlane32_swap_b32_e32 v121, v153
	v_permlane32_swap_b32_e32 v137, v169
	v_permlane32_swap_b32_e32 v122, v154
	v_permlane32_swap_b32_e32 v138, v170
	v_permlane32_swap_b32_e32 v123, v155
	v_permlane32_swap_b32_e32 v139, v171
	v_permlane32_swap_b32_e32 v124, v156
	v_permlane32_swap_b32_e32 v140, v172
	v_permlane32_swap_b32_e32 v125, v157
	v_permlane32_swap_b32_e32 v141, v173
	v_permlane32_swap_b32_e32 v126, v158
	v_permlane32_swap_b32_e32 v142, v174
	v_permlane32_swap_b32_e32 v127, v159
	v_permlane32_swap_b32_e32 v143, v175
	v_permlane32_swap_b32_e32 v128, v160
	v_permlane32_swap_b32_e32 v144, v176
	v_permlane32_swap_b32_e32 v129, v161
	v_permlane32_swap_b32_e32 v145, v177
	v_permlane32_swap_b32_e32 v130, v162
	v_permlane32_swap_b32_e32 v146, v178
	v_permlane32_swap_b32_e32 v131, v163
	v_permlane32_swap_b32_e32 v147, v179
	v_fma_f32 v116, v34, v54, v116
	v_fma_f32 v132, v34, v55, v132
	v_fma_f32 v116, -v35, v55, v116
	v_fma_f32 v132, v35, v54, v132
	v_fma_f32 v117, v34, v116, v117
	v_fma_f32 v133, v34, v132, v133
	v_fma_f32 v117, -v35, v132, v117
	v_fma_f32 v133, v35, v116, v133
	v_fma_f32 v118, v34, v117, v118
	v_fma_f32 v134, v34, v133, v134
	v_fma_f32 v118, -v35, v133, v118
	v_fma_f32 v134, v35, v117, v134
	v_fma_f32 v119, v34, v118, v119
	v_fma_f32 v135, v34, v134, v135
	v_fma_f32 v119, -v35, v134, v119
	v_fma_f32 v135, v35, v118, v135
	v_fma_f32 v148, v34, v119, v148
	v_fma_f32 v164, v34, v135, v164
	v_fma_f32 v148, -v35, v135, v148
	v_fma_f32 v164, v35, v119, v164
	v_fma_f32 v149, v34, v148, v149
	v_fma_f32 v165, v34, v164, v165
	v_fma_f32 v149, -v35, v164, v149
	v_fma_f32 v165, v35, v148, v165
	v_fma_f32 v150, v34, v149, v150
	v_fma_f32 v166, v34, v165, v166
	v_fma_f32 v150, -v35, v165, v150
	v_fma_f32 v166, v35, v149, v166
	v_fma_f32 v151, v34, v150, v151
	v_fma_f32 v167, v34, v166, v167
	v_fma_f32 v151, -v35, v166, v151
	v_fma_f32 v167, v35, v150, v167
	v_fma_f32 v120, v34, v151, v120
	v_fma_f32 v136, v34, v167, v136
	v_fma_f32 v120, -v35, v167, v120
	v_fma_f32 v136, v35, v151, v136
	v_fma_f32 v121, v34, v120, v121
	v_fma_f32 v137, v34, v136, v137
	v_fma_f32 v121, -v35, v136, v121
	v_fma_f32 v137, v35, v120, v137
	v_fma_f32 v122, v34, v121, v122
	v_fma_f32 v138, v34, v137, v138
	v_fma_f32 v122, -v35, v137, v122
	v_fma_f32 v138, v35, v121, v138
	v_fma_f32 v123, v34, v122, v123
	v_fma_f32 v139, v34, v138, v139
	v_fma_f32 v123, -v35, v138, v123
	v_fma_f32 v139, v35, v122, v139
	v_fma_f32 v152, v34, v123, v152
	v_fma_f32 v168, v34, v139, v168
	v_fma_f32 v152, -v35, v139, v152
	v_fma_f32 v168, v35, v123, v168
	v_fma_f32 v153, v34, v152, v153
	v_fma_f32 v169, v34, v168, v169
	v_fma_f32 v153, -v35, v168, v153
	v_fma_f32 v169, v35, v152, v169
	v_fma_f32 v154, v34, v153, v154
	v_fma_f32 v170, v34, v169, v170
	v_fma_f32 v154, -v35, v169, v154
	v_fma_f32 v170, v35, v153, v170
	v_fma_f32 v155, v34, v154, v155
	v_fma_f32 v171, v34, v170, v171
	v_fma_f32 v155, -v35, v170, v155
	v_fma_f32 v171, v35, v154, v171
	v_fma_f32 v124, v34, v155, v124
	v_fma_f32 v140, v34, v171, v140
	v_fma_f32 v124, -v35, v171, v124
	v_fma_f32 v140, v35, v155, v140
	v_fma_f32 v125, v34, v124, v125
	v_fma_f32 v141, v34, v140, v141
	v_fma_f32 v125, -v35, v140, v125
	v_fma_f32 v141, v35, v124, v141
	v_fma_f32 v126, v34, v125, v126
	v_fma_f32 v142, v34, v141, v142
	v_fma_f32 v126, -v35, v141, v126
	v_fma_f32 v142, v35, v125, v142
	v_fma_f32 v127, v34, v126, v127
	v_fma_f32 v143, v34, v142, v143
	v_fma_f32 v127, -v35, v142, v127
	v_fma_f32 v143, v35, v126, v143
	v_fma_f32 v156, v34, v127, v156
	v_fma_f32 v172, v34, v143, v172
	v_fma_f32 v156, -v35, v143, v156
	v_fma_f32 v172, v35, v127, v172
	v_fma_f32 v157, v34, v156, v157
	v_fma_f32 v173, v34, v172, v173
	v_fma_f32 v157, -v35, v172, v157
	v_fma_f32 v173, v35, v156, v173
	v_fma_f32 v158, v34, v157, v158
	v_fma_f32 v174, v34, v173, v174
	v_fma_f32 v158, -v35, v173, v158
	v_fma_f32 v174, v35, v157, v174
	v_fma_f32 v159, v34, v158, v159
	v_fma_f32 v175, v34, v174, v175
	v_fma_f32 v159, -v35, v174, v159
	v_fma_f32 v175, v35, v158, v175
	v_fma_f32 v128, v34, v159, v128
	v_fma_f32 v144, v34, v175, v144
	v_fma_f32 v128, -v35, v175, v128
	v_fma_f32 v144, v35, v159, v144
	v_fma_f32 v129, v34, v128, v129
	v_fma_f32 v145, v34, v144, v145
	v_fma_f32 v129, -v35, v144, v129
	v_fma_f32 v145, v35, v128, v145
	v_fma_f32 v130, v34, v129, v130
	v_fma_f32 v146, v34, v145, v146
	v_fma_f32 v130, -v35, v145, v130
	v_fma_f32 v146, v35, v129, v146
	v_fma_f32 v131, v34, v130, v131
	v_fma_f32 v147, v34, v146, v147
	v_fma_f32 v131, -v35, v146, v131
	v_fma_f32 v147, v35, v130, v147
	v_fma_f32 v160, v34, v131, v160
	v_fma_f32 v176, v34, v147, v176
	v_fma_f32 v160, -v35, v147, v160
	v_fma_f32 v176, v35, v131, v176
	v_fma_f32 v161, v34, v160, v161
	v_fma_f32 v177, v34, v176, v177
	v_fma_f32 v161, -v35, v176, v161
	v_fma_f32 v177, v35, v160, v177
	v_fma_f32 v162, v34, v161, v162
	v_fma_f32 v178, v34, v177, v178
	v_fma_f32 v162, -v35, v177, v162
	v_fma_f32 v178, v35, v161, v178
	v_fma_f32 v163, v34, v162, v163
	v_fma_f32 v179, v34, v178, v179
	v_fma_f32 v163, -v35, v178, v163
	v_fma_f32 v179, v35, v162, v179
	v_mov_b32_e32 v54, v163
	v_mov_b32_e32 v55, v179
	global_store_dwordx2 v[66:67], v[54:55], off
	v_readlane_b32 s0, v251, 20
	s_add_i32 s2, s2, s0
	s_cmpk_gt_i32 s2, 0x3fff
	s_cbranch_scc0 .Ls5p1_job
	s_waitcnt vmcnt(0)
